# attn_c items: waves 4-7 run at s_setprio 1 (static, no per-segment flips)
# speedup vs baseline: 1.0053x; 1.0053x over previous
; DI void phase_attn_c(const Params& P, int l, char* shm, int dry) {
;     ...
;   for (int it = blockIdx.x; it < 256; it += gridDim.x) {
;     const int bh = it >> 4, pr = it & 15, b = bh >> 2, h = bh & 3;
; #pragma clang loop unroll(disable)
;     for (int hf = 0; hf < 2; ++hf) attn_c_item(P, l, b, h, hf ? pr : 31 - pr, shm, B2, dry);
.LBB0_575:
	v_readfirstlane_b32 s98, v135
	s_nop 0
	s_cmp_lt_u32 s98, 0x100
	s_cbranch_scc1 .Lsp_skipc
	s_setprio 1

; DI int tid_() { int t = threadIdx.x; asm volatile("" : "+v"(t)); return t; }
; #define PH(...)                                                     \
;   {                                                                 \
;     Params Q = P;                                                   \
;     asm volatile("" : "+s"(Q.ws), "+s"(Q.out), "+s"(Q.x));        \
;     __VA_ARGS__;                                                    \
;   }
; #define GSYNC(k) xbar(P.ws, ++bgen, xcc, nloc, nx)
; template <int MODE>
; DI void phase_inproj(const Params& P, char* shm) {
;   const u16* hb = (const u16*)(P.ws + OFF_HB);
;   const u16* W = (const u16*)(P.ws + OFF_W) + W_IN;
;   constexpr int wrow = MODE == 0 ? WR_C : MODE == 1 ? WR_D : MODE == 2 ? WR_A : WR_B;
;   constexpr int nN = MODE == 0 ? 4 : MODE == 1 ? 8 : MODE == 2 ? 6 : 4;
;   constexpr int SILU0 = MODE == 0 ? 512 : MODE == 1 ? 1536 : MODE == 2 ? 1024 : 512;
;   const int tid = tid_(), lane = tid & 63, wid = tid >> 6, wr = wid >> 2, wc = wid & 3, fr = lane & 15, fq = lane >> 4;
;   for (int tl = blockIdx.x; tl < 128 * nN; tl += gridDim.x) {
; __global__ void __launch_bounds__(512) fwd_megakernel(Params P) {
;     ...
;     PH(phase_attn_c(Q, l, shm, 0));
;     ...
;     PH(phase_inproj<2>(Q, shm));
;     PH(phase_inproj<3>(Q, shm));
;     GSYNC(11);
;     ...
;     PH(phase_inproj<2>(Q, shm));
;     PH(phase_inproj<3>(Q, shm));
.LBB0_584:
	s_setprio 0
	v_readlane_b32 s12, v253, 2
	v_readlane_b32 s13, v253, 3
	s_mov_b64 s[0:1], s[66:67]
	s_mov_b64 s[8:9], s[54:55]
	s_mov_b64 s[4:5], s[12:13]
	v_readlane_b32 s24, v253, 14
	v_readlane_b32 s0, v252, 0
	v_readlane_b32 s25, v253, 15
	v_readlane_b32 s1, v252, 1
	v_mov_b32_e32 v0, v135
	s_andn2_b64 vcc, exec, s[0:1]
	s_mov_b64 s[24:25], 0x6fff800
	v_readlane_b32 s14, v253, 4
	v_readlane_b32 s15, v253, 5
	v_readlane_b32 s16, v253, 6
	v_readlane_b32 s17, v253, 7
	v_readlane_b32 s18, v253, 8
	v_readlane_b32 s19, v253, 9
	v_readlane_b32 s20, v253, 10
	v_readlane_b32 s21, v253, 11
	v_readlane_b32 s22, v253, 12
	v_readlane_b32 s23, v253, 13
	v_readlane_b32 s26, v253, 16
	v_readlane_b32 s27, v253, 17
	s_cbranch_vccnz .LBB0_673
	s_add_u32 s18, s8, 0x3000000
	v_and_b32_e32 v1, 15, v0
	s_waitcnt lgkmcnt(0)
	v_and_b32_e32 v2, 0xc0, v0
	v_lshrrev_b32_e32 v3, 1, v0
	v_lshrrev_b32_e32 v0, 2, v0
	s_addc_u32 s19, s9, 0
	v_and_or_b32 v1, v3, s61, v1
	v_and_or_b32 v0, v0, 12, v2
	s_add_u32 s10, s8, 0x19000000
	v_mul_lo_u32 v1, v1, s68
	v_lshlrev_b32_e32 v0, 1, v0
	s_addc_u32 s11, s9, 0
	v_add_u32_e32 v130, v1, v0
	s_mov_b32 s20, s47
	s_branch .LBB0_587

; DI int tid_() { int t = threadIdx.x; asm volatile("" : "+v"(t)); return t; }
; template <int MF, int NF, bool SWAP = true>
; DI void gemm_main(f32x4 (&acc)[MF][NF], const u16* __restrict__ Ab, int lda, const u16* __restrict__ Bb, int ldb,
;                   int K, char* shm) {
;   constexpr bool RING3 = (NF == 2);
;   constexpr int TILE_A = 32768, STAGE = RING3 ? 49152 : 65536;
;   const int tid = tid_(), wid = tid >> 6, lane = tid & 63, wr = wid >> 2, wc = wid & 3, fr = lane & 15,
;             fq = lane >> 4;
;   constexpr int AL = MF / 2;
;   int sR0, sC0;
;   stage_rc<2>(wid * 1024 + lane * 16, sR0, sC0);
; #pragma unroll
;   for (int m = 0; m < MF; ++m)
; #pragma unroll
;     for (int n = 0; n < NF; ++n) acc[m][n] = f32x4{0.f, 0.f, 0.f, 0.f};
;   const int nt = K >> 6;
;   const int pa0 = sR0 * lda + sC0, pb0 = sR0 * ldb + sC0;
;     ...
;   const int a_off = lds_byte<2>(fr, fq * 8) + wr * (MF * 2048);
;   const int b_off = lds_byte<2>(fr, fq * 8) + wc * (NF * 2048);
;   G_STAGE(0, 0);
;   if constexpr (RING3) {
;     if (nt > 1) { G_STAGE(1, 1); asm volatile("s_waitcnt vmcnt(6)" ::: "memory"); }
;     else asm volatile("s_waitcnt vmcnt(0)" ::: "memory");
;     asm volatile("s_waitcnt lgkmcnt(0)" ::: "memory");
;     __builtin_amdgcn_s_barrier();
;   } else {
;     asm volatile("s_waitcnt vmcnt(0)" ::: "memory");
;     __syncthreads();
;   }
.LBB0_587:
	s_ashr_i32 s0, s20, 31
	s_lshr_b32 s0, s0, 29
	s_add_i32 s0, s20, s0
	s_ashr_i32 s1, s0, 3
	s_and_b32 s0, s0, -8
	s_sub_i32 s0, s20, s0
	s_lshr_b32 s4, s0, 31
	s_or_b32 s4, s4, 0x60
	s_mul_i32 s0, s4, s0
	s_add_i32 s0, s0, s1
	s_mul_hi_i32 s1, s0, 0x2aaaaaab
	s_lshr_b32 s4, s1, 31
	s_ashr_i32 s1, s1, 3
	s_add_i32 s1, s1, s4
	s_lshl_b32 s4, s1, 3
	s_sub_i32 s5, 0x80, s4
	s_min_u32 s5, s5, 8
	s_mul_i32 s1, s1, 48
	s_sub_i32 s12, s0, s1
	v_cvt_f32_ubyte0_e32 v1, s5
	v_cvt_f32_i32_e32 v0, s12
	v_rcp_iflag_f32_e32 v2, v1
	s_ashr_i32 s0, s12, 30
	s_or_b32 s13, s0, 1
	v_mov_b32_e32 v10, v135
	v_mul_f32_e32 v2, v0, v2
	v_trunc_f32_e32 v2, v2
	v_fma_f32 v0, -v2, v1, v0
	v_cvt_i32_f32_e32 v2, v2
	v_cmp_ge_f32_e64 s[0:1], |v0|, v1
	s_and_b64 s[0:1], s[0:1], exec
	s_cselect_b32 s0, s13, 0
	v_readfirstlane_b32 s1, v2
	s_add_i32 s0, s1, s0
	s_lshl_b32 s17, s0, 24
	s_sext_i32_i8 s1, s0
	s_mul_i32 s0, s0, s5
	s_sub_i32 s0, s12, s0
	v_lshlrev_b32_e32 v0, 4, v10
	v_and_b32_e32 v2, 32, v10
	v_ashrrev_i32_e32 v11, 6, v10
	v_lshrrev_b32_e32 v3, 31, v10
	v_bitop3_b32 v0, v0, v2, 48 bitop3:0x6c
	s_sext_i32_i8 s0, s0
	v_add_u32_e32 v3, v11, v3
	v_lshrrev_b32_e32 v13, 1, v0
	v_lshlrev_b32_e32 v0, 8, v10
	s_add_i32 s4, s4, s0
	v_and_b32_e32 v1, 15, v10
	v_ashrrev_i32_e32 v12, 1, v3
	v_and_b32_e32 v3, 0x7fffffe, v3
	v_and_b32_e32 v14, 0x3c00, v0
	s_lshl_b32 s12, s4, 8
	v_sub_u32_e32 v3, v11, v3
	v_lshl_or_b32 v0, v12, 14, v14
	v_lshlrev_b32_e32 v15, 6, v1
	v_lshlrev_b32_e32 v1, 2, v10
	s_ashr_i32 s13, s12, 31
	v_lshl_add_u32 v0, v3, 5, v0
	v_and_b32_e32 v16, 32, v1
	v_lshlrev_b32_e32 v1, 6, v10
	s_lshl_b32 s14, s1, 8
	s_lshl_b64 s[0:1], s[12:13], 11
	v_or_b32_e32 v0, v0, v13
	v_and_b32_e32 v129, 0xffffc000, v1
	v_lshlrev_b32_e32 v1, 13, v11
	s_add_u32 s0, s18, s0
	v_lshlrev_b32_e32 v128, 10, v11
	v_and_b32_e32 v131, 0x6000, v1
	v_ashrrev_i32_e32 v1, 31, v0
	s_addc_u32 s1, s19, s1
	v_lshlrev_b64 v[2:3], 1, v[0:1]
	v_readfirstlane_b32 s13, v128
	v_lshl_add_u64 v[4:5], s[0:1], 0, v[2:3]
	s_mov_b32 m0, s13
	v_add_u32_e32 v1, 0x2000, v128
	v_add_u32_e32 v0, 0x20000, v0
	global_load_lds_dwordx4 v[4:5], off
	v_lshl_add_u64 v[4:5], v[2:3], 0, s[34:35]
	v_readfirstlane_b32 s13, v1
	v_ashrrev_i32_e32 v1, 31, v0
	v_add_u32_e32 v8, 0x4000, v128
	v_lshl_add_u64 v[6:7], s[0:1], 0, v[4:5]
	s_mov_b32 m0, s13
	v_lshlrev_b64 v[0:1], 1, v[0:1]
	v_readfirstlane_b32 s13, v8
	global_load_lds_dwordx4 v[6:7], off
	v_lshl_add_u64 v[6:7], s[0:1], 0, v[0:1]
	s_mov_b32 m0, s13
	v_add_u32_e32 v17, 0x6000, v128
	global_load_lds_dwordx4 v[6:7], off
	v_lshl_add_u64 v[6:7], v[2:3], 0, s[86:87]
	v_readfirstlane_b32 s13, v17
	s_ashr_i32 s15, s14, 31
	v_lshl_add_u64 v[8:9], s[0:1], 0, v[6:7]
	s_mov_b32 m0, s13
	s_lshl_b64 s[4:5], s[14:15], 11
	global_load_lds_dwordx4 v[8:9], off
	v_and_b32_e32 v8, 48, v10
	s_add_u32 s4, s8, s4
	v_bitop3_b32 v132, v15, v16, v8 bitop3:0x36
	v_add_u32_e32 v8, 0x8000, v128
	s_addc_u32 s5, s9, s5
	v_readfirstlane_b32 s13, v8
	v_lshl_add_u64 v[2:3], s[4:5], 0, v[2:3]
	s_mov_b32 m0, s13
	v_lshl_add_u64 v[0:1], s[4:5], 0, v[0:1]
	global_load_lds_dwordx4 v[2:3], off
	v_lshl_add_u64 v[2:3], s[4:5], 0, v[4:5]
	v_add_u32_e32 v4, 0xa000, v128
	s_mov_b32 s16, 0
	v_readfirstlane_b32 s13, v4
	s_mov_b32 m0, s13
	s_mov_b32 s15, 0
	global_load_lds_dwordx4 v[2:3], off
	v_add_u32_e32 v2, 0xc000, v128
	s_nop 0
	v_readfirstlane_b32 s13, v2
	v_add_u32_e32 v2, 0xe000, v128
	s_mov_b32 m0, s13
	v_readfirstlane_b32 s13, v2
	global_load_lds_dwordx4 v[0:1], off
	v_lshl_add_u64 v[0:1], s[4:5], 0, v[6:7]
	s_mov_b32 m0, s13
	s_mov_b32 s13, 0
	global_load_lds_dwordx4 v[0:1], off
	v_mul_lo_u32 v0, v12, s70
	s_waitcnt vmcnt(0)
	v_or_b32_e32 v0, v13, v0
	v_lshlrev_b32_e32 v1, 5, v11
	v_add3_u32 v136, v0, v14, v1
	v_mov_b32_e32 v0, 0
	v_mov_b32_e32 v1, v0
	v_mov_b32_e32 v2, v0
	v_mov_b32_e32 v3, v0
	v_mov_b32_e32 v4, v0
	v_mov_b32_e32 v5, v0
	v_mov_b32_e32 v6, v0
	v_mov_b32_e32 v7, v0
	v_mov_b32_e32 v8, v0
	v_mov_b32_e32 v9, v0
	v_mov_b32_e32 v10, v0
	v_mov_b32_e32 v11, v0
	v_mov_b32_e32 v12, v0
	v_mov_b32_e32 v13, v0
	v_mov_b32_e32 v14, v0
	v_mov_b32_e32 v15, v0
	v_mov_b32_e32 v16, v0
	v_mov_b32_e32 v17, v0
	v_mov_b32_e32 v18, v0
	v_mov_b32_e32 v19, v0
	v_mov_b32_e32 v20, v0
	v_mov_b32_e32 v21, v0
	v_mov_b32_e32 v22, v0
	v_mov_b32_e32 v23, v0
	v_mov_b32_e32 v24, v0
	v_mov_b32_e32 v25, v0
	v_mov_b32_e32 v26, v0
	v_mov_b32_e32 v27, v0
	v_mov_b32_e32 v28, v0
	v_mov_b32_e32 v29, v0
	v_mov_b32_e32 v30, v0
	v_mov_b32_e32 v31, v0
	v_mov_b32_e32 v32, v0
	v_mov_b32_e32 v33, v0
	v_mov_b32_e32 v34, v0
	v_mov_b32_e32 v35, v0
	v_mov_b32_e32 v36, v0
	v_mov_b32_e32 v37, v0
	v_mov_b32_e32 v38, v0
	v_mov_b32_e32 v39, v0
	v_mov_b32_e32 v40, v0
	v_mov_b32_e32 v41, v0
	v_mov_b32_e32 v42, v0
	v_mov_b32_e32 v43, v0
	v_mov_b32_e32 v44, v0
	v_mov_b32_e32 v45, v0
	v_mov_b32_e32 v46, v0
	v_mov_b32_e32 v47, v0
	v_mov_b32_e32 v48, v0
	v_mov_b32_e32 v49, v0
	v_mov_b32_e32 v50, v0
	v_mov_b32_e32 v51, v0
	v_mov_b32_e32 v52, v0
	v_mov_b32_e32 v53, v0
	v_mov_b32_e32 v54, v0
	v_mov_b32_e32 v55, v0
	v_mov_b32_e32 v56, v0
	v_mov_b32_e32 v57, v0
	v_mov_b32_e32 v58, v0
	v_mov_b32_e32 v59, v0
	v_mov_b32_e32 v60, v0
	v_mov_b32_e32 v61, v0
	v_mov_b32_e32 v62, v0
	v_mov_b32_e32 v63, v0
	v_mov_b32_e32 v64, v0
	v_mov_b32_e32 v65, v0
	v_mov_b32_e32 v66, v0
	v_mov_b32_e32 v67, v0
	v_mov_b32_e32 v68, v0
	v_mov_b32_e32 v69, v0
	v_mov_b32_e32 v70, v0
	v_mov_b32_e32 v71, v0
	v_mov_b32_e32 v72, v0
	v_mov_b32_e32 v73, v0
	v_mov_b32_e32 v74, v0
	v_mov_b32_e32 v75, v0
	v_mov_b32_e32 v76, v0
	v_mov_b32_e32 v77, v0
	v_mov_b32_e32 v78, v0
	v_mov_b32_e32 v79, v0
	v_mov_b32_e32 v80, v0
	v_mov_b32_e32 v81, v0
	v_mov_b32_e32 v82, v0
	v_mov_b32_e32 v83, v0
	v_mov_b32_e32 v84, v0
	v_mov_b32_e32 v85, v0
	v_mov_b32_e32 v86, v0
	v_mov_b32_e32 v87, v0
	v_mov_b32_e32 v88, v0
	v_mov_b32_e32 v89, v0
	v_mov_b32_e32 v90, v0
	v_mov_b32_e32 v91, v0
	v_mov_b32_e32 v92, v0
	v_mov_b32_e32 v93, v0
	v_mov_b32_e32 v94, v0
	v_mov_b32_e32 v95, v0
	v_mov_b32_e32 v96, v0
	v_mov_b32_e32 v97, v0
	v_mov_b32_e32 v98, v0
	v_mov_b32_e32 v99, v0
	v_mov_b32_e32 v100, v0
	v_mov_b32_e32 v101, v0
	v_mov_b32_e32 v102, v0
	v_mov_b32_e32 v103, v0
	v_mov_b32_e32 v104, v0
	v_mov_b32_e32 v105, v0
	v_mov_b32_e32 v106, v0
	v_mov_b32_e32 v107, v0
	v_mov_b32_e32 v108, v0
	v_mov_b32_e32 v109, v0
	v_mov_b32_e32 v110, v0
	v_mov_b32_e32 v111, v0
	v_mov_b32_e32 v112, v0
	v_mov_b32_e32 v113, v0
	v_mov_b32_e32 v114, v0
	v_mov_b32_e32 v115, v0
	v_mov_b32_e32 v116, v0
	v_mov_b32_e32 v117, v0
	v_mov_b32_e32 v118, v0
	v_mov_b32_e32 v119, v0
	v_mov_b32_e32 v120, v0
	v_mov_b32_e32 v121, v0
	v_mov_b32_e32 v122, v0
	v_mov_b32_e32 v123, v0
	v_mov_b32_e32 v124, v0
	v_mov_b32_e32 v125, v0
	v_mov_b32_e32 v126, v0
	v_mov_b32_e32 v127, v0
	s_waitcnt vmcnt(0) lgkmcnt(0)
	s_barrier
	s_nop 0
	s_branch .LBB0_589
